# retention chunk loop: one static s_setprio 1 for waves 4-7 before the loop, reset after it
# baseline (speedup 1.0000x reference)
.LBB0_2424:
	s_and_b64 s[38:39], s[74:75], exec
	v_readlane_b32 s26, v253, 11
	s_cselect_b32 s26, s26, 0
	s_add_i32 s38, s27, 5
	s_waitcnt vmcnt(0)
	v_cndmask_b32_e64 v93, 0, v3, s[44:45]
	v_cvt_f32_ubyte0_e32 v3, s38
	s_lshl_b32 s70, s5, 8
	v_exp_f32_e64 v3, -v3
	s_ashr_i32 s71, s70, 31
	s_mul_i32 s5, s5, 0x102000
	v_readlane_b32 s54, v250, 37
	s_mul_hi_i32 s38, s70, 0x1020
	v_readlane_b32 s55, v250, 38
	s_add_u32 s76, s54, s5
	s_addc_u32 s77, s55, s38
	s_lshl_b32 s5, s27, 10
	s_add_u32 s5, s86, s5
	v_cndmask_b32_e64 v90, 0, v0, s[44:45]
	v_sub_f32_e32 v0, 1.0, v3
	s_addc_u32 s27, s87, 0
	s_lshl_b32 s38, s42, 1
	v_log_f32_e32 v215, v0
	s_add_u32 s5, s5, s38
	v_cndmask_b32_e64 v121, 0, v15, s[52:53]
	v_cndmask_b32_e64 v120, 0, v14, s[52:53]
	s_addc_u32 s27, s27, 0
	v_readlane_b32 s38, v254, 51
	v_mov_b32_e32 v14, v81
	v_mov_b32_e32 v15, v81
	v_cndmask_b32_e64 v105, 0, v31, s[48:49]
	v_cndmask_b32_e64 v104, 0, v30, s[48:49]
	v_cndmask_b32_e64 v103, 0, v29, s[48:49]
	v_cndmask_b32_e64 v102, 0, v28, s[48:49]
	v_cndmask_b32_e64 v109, 0, v27, s[48:49]
	v_cndmask_b32_e64 v108, 0, v26, s[48:49]
	v_cndmask_b32_e64 v107, 0, v25, s[48:49]
	v_cndmask_b32_e64 v106, 0, v24, s[48:49]
	v_cndmask_b32_e64 v113, 0, v23, s[50:51]
	v_cndmask_b32_e64 v112, 0, v22, s[50:51]
	v_cndmask_b32_e64 v111, 0, v21, s[50:51]
	v_cndmask_b32_e64 v110, 0, v20, s[50:51]
	v_cndmask_b32_e64 v117, 0, v19, s[50:51]
	v_cndmask_b32_e64 v116, 0, v18, s[50:51]
	v_cndmask_b32_e64 v115, 0, v17, s[50:51]
	v_cndmask_b32_e64 v114, 0, v16, s[50:51]
	v_cndmask_b32_e64 v119, 0, v13, s[52:53]
	v_cndmask_b32_e64 v118, 0, v12, s[52:53]
	v_cndmask_b32_e64 v125, 0, v11, s[52:53]
	v_cndmask_b32_e64 v124, 0, v10, s[52:53]
	v_cndmask_b32_e64 v123, 0, v9, s[52:53]
	v_cndmask_b32_e64 v122, 0, v8, s[52:53]
	v_cndmask_b32_e64 v89, 0, v7, s[44:45]
	v_cndmask_b32_e64 v88, 0, v6, s[44:45]
	v_cndmask_b32_e64 v87, 0, v5, s[44:45]
	v_cndmask_b32_e64 v86, 0, v4, s[44:45]
	v_cndmask_b32_e64 v92, 0, v2, s[44:45]
	v_cndmask_b32_e64 v91, 0, v1, s[44:45]
	s_add_u32 s78, s5, s38
	v_mov_b32_e32 v0, v81
	v_mov_b32_e32 v1, v81
	v_mov_b32_e32 v2, v81
	v_mov_b32_e32 v3, v81
	v_mov_b32_e32 v4, v81
	v_mov_b32_e32 v5, v81
	v_mov_b32_e32 v6, v81
	v_mov_b32_e32 v7, v81
	v_mov_b32_e32 v8, v81
	v_mov_b32_e32 v9, v81
	v_mov_b32_e32 v10, v81
	v_mov_b32_e32 v11, v81
	v_mov_b32_e32 v12, v81
	v_mov_b32_e32 v13, v81
	v_mov_b32_e32 v220, 0
	v_mov_b64_e32 v[30:31], v[14:15]
	s_mov_b32 s43, 0
	v_cndmask_b32_e64 v97, 0, v39, s[46:47]
	v_cndmask_b32_e64 v96, 0, v38, s[46:47]
	v_cndmask_b32_e64 v95, 0, v37, s[46:47]
	v_cndmask_b32_e64 v94, 0, v36, s[46:47]
	v_cndmask_b32_e64 v101, 0, v35, s[46:47]
	v_cndmask_b32_e64 v100, 0, v34, s[46:47]
	v_cndmask_b32_e64 v99, 0, v33, s[46:47]
	v_cndmask_b32_e64 v98, 0, v32, s[46:47]
	s_addc_u32 s79, s27, 0
	v_mov_b32_e32 v82, v81
	v_mov_b32_e32 v83, v81
	v_mov_b32_e32 v84, v81
	v_mov_b32_e32 v85, v81
	v_mov_b64_e32 v[28:29], v[12:13]
	v_mov_b64_e32 v[26:27], v[10:11]
	v_mov_b64_e32 v[24:25], v[8:9]
	v_mov_b64_e32 v[22:23], v[6:7]
	v_mov_b64_e32 v[20:21], v[4:5]
	v_mov_b64_e32 v[18:19], v[2:3]
	v_mov_b64_e32 v[16:17], v[0:1]
	s_mov_b32 s5, 0
	v_mov_b32_e32 v221, v220
	v_mov_b32_e32 v218, v220
	v_mov_b32_e32 v219, v220
	v_readfirstlane_b32 s98, v226
	s_nop 3
	s_lshr_b32 s98, s98, 6
	s_cmp_ge_u32 s98, 4
	s_cbranch_scc0 .Lret_prio_done
	s_setprio 1
.Lret_prio_done:
	s_waitcnt lgkmcnt(0)
	s_barrier
	s_branch .LBB0_2426

.LBB0_2527:
	s_setprio 0
	s_cmp_le_i32 s43, s26
	s_cselect_b64 s[4:5], -1, 0
	s_and_b64 s[4:5], s[74:75], s[4:5]
	v_readlane_b32 s76, v250, 13
	s_and_b64 vcc, exec, s[4:5]
	v_readlane_b32 s77, v250, 14
	v_readlane_b32 s78, v250, 15
	v_readlane_b32 s79, v250, 16
	v_readlane_b32 s80, v250, 17
	v_readlane_b32 s81, v250, 18
	v_readlane_b32 s82, v250, 19
	v_readlane_b32 s83, v250, 20
	s_cbranch_vccz .LBB0_2416
	v_mov_b32_e32 v33, v166
	s_cmp_lt_i32 s43, 1
	v_and_b32_e32 v60, -4, v33
	v_and_b32_e32 v32, 3, v33
	v_ashrrev_i32_e32 v61, 31, v60
	s_cbranch_scc1 .LBB0_2533
	s_add_i32 s4, s43, -1
	s_lshr_b32 s5, s4, 6
	s_and_b32 s19, s4, 63
	s_mul_i32 s4, s5, s96
	s_lshl_b32 s5, s5, 12
	s_add_i32 s5, s5, 0
	v_lshl_or_b32 v33, v32, 6, s19
	s_add_i32 s4, s4, s2
	s_add_i32 s5, s5, 0x1d800
	v_lshl_add_u32 v34, v33, 2, s5
	s_and_b32 s18, s4, 3
	ds_read2st64_b32 v[38:39], v34 offset1:4
	v_lshl_add_u32 v34, v60, 2, s5
	s_add_i32 s5, s18, 5
	v_cvt_f32_ubyte0_e32 v35, s5
	v_exp_f32_e64 v40, -v35
	ds_read_b128 v[34:37], v34 offset:2048
	s_ashr_i32 s5, s4, 31
	s_waitcnt lgkmcnt(1)
	v_mov_b32_e32 v42, v39
	s_lshl_b64 s[12:13], s[4:5], 19
	v_sub_f32_e32 v40, 1.0, v40
	s_waitcnt lgkmcnt(0)
	v_pk_mul_f32 v[36:37], v[36:37], v[42:43] op_sel_hi:[1,0]
	v_pk_mul_f32 v[34:35], v[34:35], v[42:43] op_sel_hi:[1,0]
	s_add_u32 s12, s14, s12
	s_waitcnt vmcnt(0)
	v_pk_fma_f32 v[36:37], v[84:85], v[40:41], v[36:37] op_sel_hi:[1,0,1]
	v_pk_fma_f32 v[34:35], v[82:83], v[40:41], v[34:35] op_sel_hi:[1,0,1]
	s_addc_u32 s13, s6, s13
	v_lshlrev_b32_e32 v40, 11, v33
	v_mov_b32_e32 v41, v81
	v_lshl_add_u64 v[40:41], s[12:13], 0, v[40:41]
	v_lshl_add_u64 v[40:41], v[60:61], 2, v[40:41]
	v_pk_fma_f32 v[218:219], v[38:39], v[36:37], v[218:219] op_sel_hi:[0,1,1]
	s_cmp_lg_u32 s19, 63
	v_pk_fma_f32 v[220:221], v[38:39], v[34:35], v[220:221] op_sel_hi:[0,1,1]
	global_store_dwordx4 v[40:41], v[34:37], off nt
	s_cbranch_scc1 .LBB0_2533
	v_add_f32_dpp v33, v220, v220 quad_perm:[1,0,3,2] row_mask:0xf bank_mask:0xf bound_ctrl:1
	v_mov_b32_e32 v34, v81
	v_add_f32_dpp v35, v221, v221 quad_perm:[1,0,3,2] row_mask:0xf bank_mask:0xf bound_ctrl:1
	v_mov_b32_e32 v36, v81
	v_add_f32_dpp v37, v218, v218 quad_perm:[1,0,3,2] row_mask:0xf bank_mask:0xf bound_ctrl:1
	v_mov_b32_e32 v38, v81
	v_add_f32_dpp v39, v219, v219 quad_perm:[1,0,3,2] row_mask:0xf bank_mask:0xf bound_ctrl:1
	v_mov_b32_e32 v40, v81
	v_mov_b32_dpp v34, v33 quad_perm:[2,3,0,1] row_mask:0xf bank_mask:0xf
	v_mov_b32_dpp v36, v35 quad_perm:[2,3,0,1] row_mask:0xf bank_mask:0xf
	v_mov_b32_dpp v38, v37 quad_perm:[2,3,0,1] row_mask:0xf bank_mask:0xf
	v_mov_b32_dpp v40, v39 quad_perm:[2,3,0,1] row_mask:0xf bank_mask:0xf
	v_cmp_eq_u32_e32 vcc, 0, v32
	s_and_saveexec_b64 s[12:13], vcc
	s_cbranch_execz .LBB0_2532
	s_ashr_i32 s4, s4, 2
	s_ashr_i32 s5, s4, 31
	s_lshl_b64 s[4:5], s[4:5], 12
	s_add_u32 s4, s86, s4
	s_addc_u32 s5, s87, s5
	s_lshl_b32 s18, s18, 10
	s_add_u32 s4, s4, s18
	v_add_f32_e32 v37, v37, v38
	v_add_f32_e32 v35, v35, v36
	s_addc_u32 s5, s5, 0
	v_add_f32_e32 v39, v39, v40
	v_add_f32_e32 v33, v33, v34
	v_cvt_pk_bf16_f32 v34, v33, v35
	v_cvt_pk_bf16_f32 v35, v37, v39
	v_lshl_add_u64 v[36:37], v[60:61], 1, s[4:5]
	v_add_co_u32_e32 v36, vcc, 0x4080000, v36
	s_nop 1
	v_addc_co_u32_e32 v37, vcc, 0, v37, vcc
	global_store_dwordx2 v[36:37], v[34:35], off
